# prologue job list rebalanced (workgroups 192..255 take 16 extra transposes, mod-job workgroups fewer) plus mod GEMV k-loop prefetch
# baseline (speedup 1.0000x reference)
; __device__ void prologue_phase(const Params& p, char* smem) {
;     ...
;       for (int i = threadIdx.x; i < 4096; i += NTHR) {
;         const int e = j * 4096 + i;
;         const int s = e >> 5, idx = e & 31;
;         const int row = s >> 6, col = s & 63;
;         const int fi = idx & 15;
;         const float inv = powf(10000.f, -2.0f * (float)fi / 32.f);
;         const float ang = (idx < 16 ? (float)row : (float)col) * inv;
;         p.ropec[e] = cosf(ang);
;         p.ropes[e] = sinf(ang);
;       }
.LBB0_5:
	s_or_b64 exec, exec, s[2:3]
	s_load_dwordx16 s[60:75], s[0:1], 0x0
	s_cmpk_gt_i32 s57, 0x19d1
	s_waitcnt lgkmcnt(0)
	v_writelane_b32 v252, s60, 16
	s_nop 1
	v_writelane_b32 v252, s61, 17
	v_writelane_b32 v252, s62, 18
	v_writelane_b32 v252, s63, 19
	v_writelane_b32 v252, s64, 20
	v_writelane_b32 v252, s65, 21
	v_writelane_b32 v252, s66, 22
	v_writelane_b32 v252, s67, 23
	v_writelane_b32 v252, s68, 24
	v_writelane_b32 v252, s69, 25
	v_writelane_b32 v252, s70, 26
	v_writelane_b32 v252, s71, 27
	v_writelane_b32 v252, s72, 28
	v_writelane_b32 v252, s73, 29
	v_writelane_b32 v252, s74, 30
	v_writelane_b32 v252, s75, 31
	s_load_dwordx16 s[60:75], s[0:1], 0x40
	s_waitcnt lgkmcnt(0)
	v_writelane_b32 v252, s60, 32
	s_nop 1
	v_writelane_b32 v252, s61, 33
	v_writelane_b32 v252, s62, 34
	v_writelane_b32 v252, s63, 35
	v_writelane_b32 v252, s64, 36
	v_writelane_b32 v252, s65, 37
	v_writelane_b32 v252, s66, 38
	v_writelane_b32 v252, s67, 39
	v_writelane_b32 v252, s68, 40
	v_writelane_b32 v252, s69, 41
	v_writelane_b32 v252, s70, 42
	v_writelane_b32 v252, s71, 43
	v_writelane_b32 v252, s72, 44
	v_writelane_b32 v252, s73, 45
	v_writelane_b32 v252, s74, 46
	v_writelane_b32 v252, s75, 47
	s_cbranch_scc1 .LBB0_55
	v_and_b32_e32 v16, 15, v234
	v_cvt_f32_ubyte0_e32 v1, v16
	v_mul_f32_e32 v1, -2.0, v1
	v_mul_f32_e32 v1, 0x3d000000, v1
	v_mov_b32_e32 v2, 0x461c4000
	v_cmp_eq_f32_e32 vcc, 0, v1
	s_mov_b32 s2, 0x3f2aaaab
	s_movk_i32 s6, 0x204
	v_cndmask_b32_e64 v12, v2, 1.0, vcc
	v_frexp_mant_f32_e32 v2, v12
	v_cmp_gt_f32_e64 s[4:5], s2, v2
	s_mov_b32 s2, 0x3f317218
	s_mov_b32 s3, 0x42b17218
	v_cndmask_b32_e64 v3, 1.0, 2.0, s[4:5]
	v_mul_f32_e32 v2, v2, v3
	v_add_f32_e32 v5, 1.0, v2
	v_rcp_f32_e32 v10, v5
	v_add_f32_e32 v3, -1.0, v5
	v_sub_f32_e32 v7, v2, v3
	v_add_f32_e32 v3, -1.0, v2
	v_mul_f32_e32 v11, v3, v10
	v_mul_f32_e32 v4, v5, v11
	v_fma_f32 v6, v11, v5, -v4
	v_fmac_f32_e32 v6, v11, v7
	v_add_f32_e32 v2, v4, v6
	v_sub_f32_e32 v5, v3, v2
	v_pk_add_f32 v[8:9], v[2:3], v[4:5] neg_lo:[0,1] neg_hi:[0,1]
	v_mov_b32_e32 v7, v2
	v_pk_add_f32 v[2:3], v[8:9], v[6:7] neg_lo:[0,1] neg_hi:[0,1]
	v_mov_b32_e32 v6, 0x3e91f4c4
	v_add_f32_e32 v2, v2, v3
	v_add_f32_e32 v2, v5, v2
	v_mul_f32_e32 v3, v10, v2
	v_add_f32_e32 v2, v11, v3
	v_sub_f32_e32 v4, v2, v11
	v_sub_f32_e32 v13, v3, v4
	v_mul_f32_e32 v3, v2, v2
	v_fma_f32 v5, v2, v2, -v3
	v_add_f32_e32 v4, v13, v13
	v_fmac_f32_e32 v5, v2, v4
	v_add_f32_e32 v4, v3, v5
	v_fmac_f32_e32 v6, 0x3e76c4e1, v4
	v_fmaak_f32 v6, v4, v6, 0x3ecccdef
	v_sub_f32_e32 v3, v4, v3
	v_sub_f32_e32 v14, v5, v3
	v_mul_f32_e32 v3, v4, v6
	v_fma_f32 v5, v4, v6, -v3
	v_fmac_f32_e32 v5, v14, v6
	v_add_f32_e32 v6, v3, v5
	v_add_f32_e32 v7, 0x3f2aaaaa, v6
	v_sub_f32_e32 v3, v6, v3
	v_sub_f32_e32 v3, v5, v3
	v_add_f32_e32 v5, 0xbf2aaaaa, v7
	v_add_f32_e32 v3, 0x31739010, v3
	v_sub_f32_e32 v5, v6, v5
	v_pk_mul_f32 v[8:9], v[2:3], v[4:5]
	v_pk_add_f32 v[10:11], v[2:3], v[4:5]
	v_fma_f32 v6, v4, v2, -v8
	v_fmac_f32_e32 v6, v4, v13
	v_mov_b32_e32 v9, v11
	v_fmac_f32_e32 v6, v14, v2
	v_pk_add_f32 v[4:5], v[8:9], v[6:7]
	v_ldexp_f32 v14, v13, 1
	v_sub_f32_e32 v3, v4, v8
	v_sub_f32_e32 v3, v6, v3
	v_sub_f32_e32 v6, v7, v5
	v_add_f32_e32 v9, v11, v6
	v_pk_mul_f32 v[6:7], v[4:5], v[4:5] op_sel:[0,1] op_sel_hi:[1,0]
	v_cvt_f64_f32_e32 v[10:11], v12
	v_frexp_exp_i32_f64_e32 v7, v[10:11]
	v_subbrev_co_u32_e64 v7, s[4:5], 0, v7, s[4:5]
	v_cvt_f32_i32_e32 v7, v7
	v_fma_f32 v8, v4, v5, -v6
	v_fmac_f32_e32 v8, v4, v9
	v_fmac_f32_e32 v8, v3, v5
	v_mul_f32_e32 v4, 0x3f317218, v7
	v_fma_f32 v3, v7, s2, -v4
	v_fmamk_f32 v10, v7, 0xb102e308, v3
	v_ldexp_f32 v11, v2, 1
	v_add_f32_e32 v5, v6, v8
	v_pk_add_f32 v[2:3], v[4:5], v[10:11]
	v_mov_b32_e32 v12, v5
	v_mov_b32_e32 v13, v3
	v_mov_b32_e32 v7, v11
	v_pk_add_f32 v[6:7], v[12:13], v[6:7] neg_lo:[0,1] neg_hi:[0,1]
	v_mov_b32_e32 v9, v5
	v_pk_add_f32 v[6:7], v[8:9], v[6:7] neg_lo:[0,1] neg_hi:[0,1]
	v_mov_b32_e32 v11, v2
	v_add_f32_e32 v5, v14, v6
	v_add_f32_e32 v5, v5, v7
	v_pk_add_f32 v[6:7], v[2:3], v[4:5] neg_lo:[0,1] neg_hi:[0,1]
	v_pk_add_f32 v[8:9], v[2:3], v[4:5]
	v_mov_b32_e32 v4, v5
	v_mov_b32_e32 v7, v9
	v_pk_add_f32 v[12:13], v[10:11], v[6:7] neg_lo:[0,1] neg_hi:[0,1]
	v_pk_add_f32 v[6:7], v[10:11], v[6:7]
	v_mov_b32_e32 v5, v2
	v_pk_add_f32 v[10:11], v[6:7], v[2:3] op_sel:[1,0] op_sel_hi:[0,1] neg_lo:[0,1] neg_hi:[0,1]
	v_pk_add_f32 v[14:15], v[8:9], v[10:11] op_sel_hi:[1,0] neg_lo:[0,1] neg_hi:[0,1]
	v_mov_b32_e32 v8, v9
	v_mov_b32_e32 v9, v7
	v_pk_mov_b32 v[10:11], v[2:3], v[10:11] op_sel:[1,0]
	v_mov_b32_e32 v14, v12
	v_pk_add_f32 v[8:9], v[8:9], v[10:11] neg_lo:[0,1] neg_hi:[0,1]
	v_mov_b32_e32 v13, v7
	v_pk_add_f32 v[2:3], v[4:5], v[8:9] neg_lo:[0,1] neg_hi:[0,1]
	s_mov_b32 s2, 0x7f800000
	v_pk_add_f32 v[4:5], v[14:15], v[2:3]
	s_load_dwordx16 s[60:75], s[0:1], 0x40
	v_pk_add_f32 v[8:9], v[4:5], v[4:5] op_sel:[0,1] op_sel_hi:[1,0]
	s_lshl_b32 s17, s58, 12
	v_pk_add_f32 v[6:7], v[6:7], v[8:9] op_sel:[1,0] op_sel_hi:[0,1]
	v_mov_b32_e32 v5, v6
	v_pk_add_f32 v[10:11], v[4:5], v[12:13] neg_lo:[0,1] neg_hi:[0,1]
	v_mov_b32_e32 v3, v8
	v_sub_f32_e32 v4, v4, v10
	v_pk_add_f32 v[2:3], v[2:3], v[10:11] neg_lo:[0,1] neg_hi:[0,1]
	v_sub_f32_e32 v4, v12, v4
	v_add_f32_e32 v2, v2, v4
	v_add_f32_e32 v2, v2, v3
	v_add_f32_e32 v3, v6, v2
	v_sub_f32_e32 v4, v3, v6
	v_sub_f32_e32 v2, v2, v4
	v_mul_f32_e32 v4, v1, v3
	v_fma_f32 v3, v1, v3, -v4
	v_fmac_f32_e32 v3, v1, v2
	v_add_f32_e32 v2, v4, v3
	v_cmp_class_f32_e64 s[4:5], v4, s6
	v_sub_f32_e32 v5, v2, v4
	v_sub_f32_e32 v3, v3, v5
	v_cndmask_b32_e64 v2, v2, v4, s[4:5]
	v_mov_b32_e32 v4, 0x37000000
	v_cmp_eq_f32_e64 s[4:5], s3, v2
	s_lshl_b32 s18, s58, 4
	s_add_i32 s20, s57, 0xffffe640
	v_cndmask_b32_e64 v4, 0, v4, s[4:5]
	v_sub_f32_e32 v5, v2, v4
	s_mov_b32 s4, 0x3fb8aa3b
	v_mul_f32_e32 v6, 0x3fb8aa3b, v5
	v_fma_f32 v7, v5, s4, -v6
	v_rndne_f32_e32 v8, v6
	v_fmamk_f32 v7, v5, 0x32a5705f, v7
	v_sub_f32_e32 v6, v6, v8
	v_add_f32_e32 v6, v6, v7
	v_exp_f32_e32 v6, v6
	v_cvt_i32_f32_e32 v7, v8
	v_cmp_neq_f32_e64 s[4:5], |v2|, s2
	s_mov_b32 s2, 0xc2ce8ed0
	v_mov_b32_e32 v75, 0
	v_cndmask_b32_e64 v2, 0, v3, s[4:5]
	v_ldexp_f32 v3, v6, v7
	v_cmp_ngt_f32_e64 s[4:5], s2, v5
	v_add_f32_e32 v2, v4, v2
	v_mov_b32_e32 v4, 0x7f800000
	v_cndmask_b32_e64 v3, 0, v3, s[4:5]
	v_cmp_nlt_f32_e64 s[4:5], s3, v5
	v_cmp_neq_f32_e64 s[2:3], v1, |v1|
	v_lshrrev_b32_e32 v111, 5, v234
	v_cndmask_b32_e64 v3, v4, v3, s[4:5]
	v_fma_f32 v2, v3, v2, v3
	v_cmp_class_f32_e64 s[4:5], v3, s6
	v_add_u32_e32 v113, 0xfffffe00, v234
	s_movk_i32 s19, 0x3840
	v_cndmask_b32_e64 v2, v2, v3, s[4:5]
	v_cndmask_b32_e64 v3, v4, 0, s[2:3]
	v_cndmask_b32_e64 v3, v3, 1.0, vcc
	v_cmp_class_f32_e64 s[2:3], v1, s6
	s_mov_b32 s21, 0xfe5163ab
	s_mov_b32 s22, 0x3c439041
	v_cndmask_b32_e64 v1, |v2|, v3, s[2:3]
	v_lshrrev_b32_e32 v2, 4, v234
	v_lshl_or_b32 v3, s57, 4, v16
	v_lshlrev_b32_e32 v74, 2, v2
	v_add_u32_e32 v78, 0xfffe6400, v3
	v_mul_hi_u32_u24_e32 v3, 0x3840, v2
	v_mul_u32_u24_e32 v2, 0x3840, v2
	v_lshl_or_b32 v2, v16, 2, v2
	s_waitcnt lgkmcnt(0)
; __device__ void prologue_phase(const Params& p, char* smem) {
;     ...
;   for (int job = blockIdx.x; job < NJ_MOD + NJ_TR + NJ_G + NJ_R; job += gridDim.x) {
;     if (job < NJ_MOD) {
;       mod_job(p, job, smem);
;     } else if (job < NJ_MOD + NJ_TR) {
;       int j = job - NJ_MOD;
	v_lshl_add_u64 v[2:3], s[60:61], 0, v[2:3]
	s_load_dwordx16 s[60:75], s[0:1], 0x0
	s_lshl_b32 s2, s57, 12
	s_add_i32 s16, s2, 0xfe63e000
	s_mov_b64 s[2:3], 0x2400
	v_lshl_add_u64 v[76:77], s[42:43], 0, v[74:75]
	s_waitcnt lgkmcnt(0)
	s_add_u32 s30, s68, 0x5a000
	v_lshl_add_u64 v[80:81], v[2:3], 0, s[2:3]
	s_addc_u32 s31, s69, 0
	s_mov_b32 s23, 0xdb629599
	s_mov_b32 s24, 0xf534ddc0
	s_mov_b32 s25, 0xfc2757d1
	s_mov_b32 s26, 0x4e441529
	s_mov_b32 s27, 0xa2f9836e
	s_mov_b32 s33, 0x3fc90fda
	s_mov_b32 s36, 0xbfc90fda
	v_mov_b32_e32 v115, 0x3c0881c4
	v_mov_b32_e32 v117, 0xbab64f3b
	s_movk_i32 s37, 0x104
	v_not_b32_e32 v122, 63
	v_not_b32_e32 v123, 31
	v_mov_b32_e32 v124, 0x7fc00000
	v_mov_b32_e32 v125, 0xe10000
	s_add_i32 s38, 0, 0x11000
	s_mov_b32 s39, s57
	s_mov_b32 s35, 0
	s_mul_i32 s100, s58, 25
	s_add_i32 s20, s20, s100
	s_lshl_b32 s100, s100, 12
	s_add_i32 s16, s16, s100
	s_mul_i32 s100, s18, 25
	v_add_u32_e32 v78, s100, v78
	s_mov_b32 s100, 0
	s_branch .LBB0_8
.LBB0_7:
	s_add_i32 s100, s100, 1
	s_cmpk_lt_u32 s57, 0xc0
	s_cbranch_scc0 .Lpj_hi
	s_cmpk_gt_u32 s100, 21
	s_cbranch_scc1 .LBB0_54
	s_lshl_b32 s39, s100, 8
	s_add_i32 s39, s39, s57
	s_addk_i32 s39, 960
	s_branch .LBB0_8
.Lpj_hi:
	s_cmpk_lt_u32 s100, 16
	s_cbranch_scc0 .Lpj_hi2
	s_lshl_b32 s39, s100, 6
	s_add_i32 s39, s39, s57
	s_branch .LBB0_8
.Lpj_hi2:
	s_cmpk_lt_u32 s100, 37
	s_cbranch_scc0 .Lpj_hi3
	s_lshl_b32 s39, s100, 8
	s_add_i32 s39, s39, s57
	s_addk_i32 s39, -2880
	s_branch .LBB0_8
.Lpj_hi3:
	s_cmpk_eq_u32 s100, 37
	s_cbranch_scc0 .LBB0_54
	s_add_i32 s39, s57, 0x1900
	s_cmpk_lt_i32 s39, 0x19d2
	s_cbranch_scc0 .LBB0_54
